# diff attention map-0 fast loop: four K/V LDS stage buffers (upper pair at +64 KiB via address bit toggled per iteration), one barrier per key tile, LDS writes moved into the P.V MFMA shadow
# speedup vs baseline: 1.0097x; 1.0097x over previous
.LBB0_796:
	s_xor_b64 s[6:7], s[0:1], -1
	s_lshl_b32 s0, s9, 3
	s_or_b32 s18, s0, 0x8000
	s_cmp_lg_u32 0, -1
	s_cselect_b32 s2, 0, 0
	s_or_b32 s12, s10, 64
	s_mov_b32 s13, s11
	v_lshl_add_u64 v[38:39], s[12:13], 0, v[144:145]
	v_mov_b64_e32 v[40:41], s[94:95]
	v_mad_u64_u32 v[40:41], s[0:1], v38, s60, v[40:41]
	v_mad_i32_i24 v41, v39, s60, v41
	v_mov_b32_e32 v33, v153
	v_lshl_add_u64 v[38:39], v[40:41], 0, v[32:33]
	v_lshl_add_u64 v[40:41], s[12:13], 0, v[146:147]
	v_mov_b64_e32 v[42:43], s[70:71]
	v_mad_u64_u32 v[42:43], s[0:1], v40, s60, v[42:43]
	v_mad_i32_i24 v43, v41, s60, v43
	v_xor_b32_e32 v64, 0x80000000, v36
	v_lshl_add_u64 v[40:41], v[42:43], 0, s[90:91]
	v_mov_b32_e32 v149, v153
	v_mov_b32_e32 v65, v64
	v_mov_b32_e32 v66, v64
	v_mov_b32_e32 v67, v64
	v_mov_b32_e32 v68, v64
	v_mov_b32_e32 v69, v64
	v_mov_b32_e32 v70, v64
	v_mov_b32_e32 v71, v64
	v_mov_b32_e32 v72, v64
	v_mov_b32_e32 v73, v64
	v_mov_b32_e32 v74, v64
	v_mov_b32_e32 v75, v64
	v_mov_b32_e32 v76, v64
	v_mov_b32_e32 v77, v64
	v_mov_b32_e32 v78, v64
	v_mov_b32_e32 v79, v64
	v_lshl_add_u64 v[46:47], v[40:41], 0, v[148:149]
	global_load_dwordx4 v[38:41], v[38:39], off offset:3072
	s_nop 0
	global_load_dwordx4 v[42:45], v[46:47], off
	v_add_co_u32_e32 v46, vcc, s58, v46
	v_sub_f32_e32 v0, v0, v36
	s_nop 0
	v_addc_co_u32_e32 v47, vcc, 0, v47, vcc
	global_load_dwordx4 v[46:49], v[46:47], off
	v_exp_f32_e32 v183, v0
	v_sub_f32_e32 v0, v1, v36
	v_exp_f32_e32 v168, v0
	v_sub_f32_e32 v0, v2, v36
	v_exp_f32_e32 v185, v0
	v_sub_f32_e32 v0, v3, v36
	v_exp_f32_e32 v166, v0
	v_sub_f32_e32 v0, v4, v36
	v_exp_f32_e32 v186, v0
	v_sub_f32_e32 v0, v5, v36
	v_exp_f32_e32 v172, v0
	v_sub_f32_e32 v0, v6, v36
	v_exp_f32_e32 v187, v0
	v_sub_f32_e32 v0, v7, v36
	v_exp_f32_e32 v170, v0
	v_sub_f32_e32 v0, v8, v36
	v_exp_f32_e32 v176, v0
	v_sub_f32_e32 v0, v9, v36
	v_exp_f32_e32 v177, v0
	v_sub_f32_e32 v0, v10, v36
	v_exp_f32_e32 v174, v0
	v_sub_f32_e32 v0, v11, v36
	v_exp_f32_e32 v175, v0
	v_sub_f32_e32 v0, v12, v36
	v_exp_f32_e32 v180, v0
	v_sub_f32_e32 v0, v13, v36
	v_and_b32_e32 v203, 63, v34
	v_exp_f32_e32 v181, v0
	v_sub_f32_e32 v0, v14, v36
	v_lshlrev_b32_e32 v37, 3, v203
	v_and_b32_e32 v35, 0xc0, v35
	v_lshlrev_b32_e32 v34, 1, v34
	v_exp_f32_e32 v178, v0
	v_sub_f32_e32 v0, v15, v36
	v_and_or_b32 v35, v37, 24, v35
	v_and_b32_e32 v34, 32, v34
	v_and_b32_e32 v37, 0x100, v37
	v_exp_f32_e32 v179, v0
	v_or3_b32 v34, v35, v34, v37
	v_add_u32_e32 v206, s2, v34
	s_addk_i32 s2, 0x4000
	v_mov_b32_e32 v204, 0
	v_sub_f32_e32 v95, v31, v36
	v_sub_f32_e32 v94, v30, v36
	v_sub_f32_e32 v93, v29, v36
	v_sub_f32_e32 v92, v28, v36
	v_sub_f32_e32 v91, v27, v36
	v_sub_f32_e32 v90, v26, v36
	v_sub_f32_e32 v89, v25, v36
	v_sub_f32_e32 v88, v24, v36
	v_sub_f32_e32 v87, v23, v36
	v_sub_f32_e32 v86, v22, v36
	v_sub_f32_e32 v85, v21, v36
	v_sub_f32_e32 v84, v20, v36
	v_sub_f32_e32 v83, v19, v36
	v_sub_f32_e32 v82, v18, v36
	v_sub_f32_e32 v81, v17, v36
	v_sub_f32_e32 v80, v16, v36
	s_waitcnt vmcnt(2)
	ds_write_b128 v209, v[38:41] offset:40960
	s_waitcnt vmcnt(1)
	ds_write_b128 v210, v[42:45] offset:16384
	s_waitcnt vmcnt(0)
	ds_write_b128 v211, v[46:49] offset:16384
	v_add_u32_e32 v205, s2, v34
	v_lshl_add_u64 v[150:151], s[94:95], 0, v[32:33]
	s_mov_b64 s[14:15], 0
	s_movk_i32 s9, 0x80
	s_mov_b32 s16, 2
	v_readfirstlane_b32 s100, v239
	s_add_i32 s48, s10, 0x80
	v_lshl_add_u64 v[244:245], s[48:49], 0, v[144:145]
	v_mad_u64_u32 v[246:247], s[0:1], v244, s60, v[150:151]
	v_mad_i32_i24 v247, v245, s60, v247
	v_lshl_add_u64 v[244:245], s[48:49], 0, v[146:147]
	v_mov_b64_e32 v[248:249], s[70:71]
	global_load_dwordx4 v[162:165], v[246:247], off offset:3072
	v_mad_u64_u32 v[246:247], s[0:1], v244, s60, v[248:249]
	v_mad_i32_i24 v247, v245, s60, v247
	s_mov_b32 s91, s49
	v_lshl_add_u64 v[244:245], v[246:247], 0, s[90:91]
	v_lshl_add_u64 v[244:245], v[244:245], 0, v[148:149]
	s_mov_b32 s0, s58
	s_mov_b32 s1, 0
	v_lshl_add_u64 v[246:247], v[244:245], 0, s[0:1]
	global_load_dwordx4 v[224:227], v[244:245], off
	global_load_dwordx4 v[232:235], v[246:247], off
	v_mov_b32_e32 v0, 0
	v_mov_b32_e32 v1, v204
	v_mov_b32_e32 v2, v204
	v_mov_b32_e32 v3, v204
	v_mov_b32_e32 v4, v204
	v_mov_b32_e32 v5, v204
	v_mov_b32_e32 v6, v204
	v_mov_b32_e32 v7, v204
	v_mov_b32_e32 v8, v204
	v_mov_b32_e32 v9, v204
	v_mov_b32_e32 v10, v204
	v_mov_b32_e32 v11, v204
	v_mov_b32_e32 v12, v204
	v_mov_b32_e32 v13, v204
	v_mov_b32_e32 v14, v204
	v_mov_b32_e32 v15, v204
	v_mov_b32_e32 v16, 0
	v_mov_b32_e32 v17, v204
	v_mov_b32_e32 v18, v204
	v_mov_b32_e32 v19, v204
	v_mov_b32_e32 v20, v204
	v_mov_b32_e32 v21, v204
	v_mov_b32_e32 v22, v204
	v_mov_b32_e32 v23, v204
	v_mov_b32_e32 v24, v204
	v_mov_b32_e32 v25, v204
	v_mov_b32_e32 v26, v204
	v_mov_b32_e32 v27, v204
	v_mov_b32_e32 v28, v204
	v_mov_b32_e32 v29, v204
	v_mov_b32_e32 v30, v204
	v_mov_b32_e32 v31, v204
	v_mov_b32_e32 v32, 0
	v_mov_b32_e32 v33, v204
	v_mov_b32_e32 v34, v204
	v_mov_b32_e32 v35, v204
	v_mov_b32_e32 v36, v204
	v_mov_b32_e32 v37, v204
	v_mov_b32_e32 v38, v204
	v_mov_b32_e32 v39, v204
	v_mov_b32_e32 v40, v204
	v_mov_b32_e32 v41, v204
	v_mov_b32_e32 v42, v204
	v_mov_b32_e32 v43, v204
	v_mov_b32_e32 v44, v204
	v_mov_b32_e32 v45, v204
	v_mov_b32_e32 v46, v204
	v_mov_b32_e32 v47, v204
	v_mov_b32_e32 v48, 0
	v_mov_b32_e32 v49, v204
	v_mov_b32_e32 v50, v204
	v_mov_b32_e32 v51, v204
	v_mov_b32_e32 v52, v204
	v_mov_b32_e32 v53, v204
	v_mov_b32_e32 v54, v204
	v_mov_b32_e32 v55, v204
	v_mov_b32_e32 v56, v204
	v_mov_b32_e32 v57, v204
	v_mov_b32_e32 v58, v204
	v_mov_b32_e32 v59, v204
	v_mov_b32_e32 v60, v204
	v_mov_b32_e32 v61, v204
	v_mov_b32_e32 v62, v204
	v_mov_b32_e32 v63, v204
	s_waitcnt lgkmcnt(0)
	s_barrier
	v_xor_b32_e32 v209, 0x10000, v209
	v_xor_b32_e32 v210, 0x10000, v210
	v_xor_b32_e32 v211, 0x10000, v211
.LBB0_797:
	ds_read_b128 v[188:191], v207 offset:45056
	ds_read_b128 v[112:115], v207 offset:40960
	v_exp_f32_e32 v152, v80
	v_exp_f32_e32 v167, v81
	v_exp_f32_e32 v169, v82
	v_exp_f32_e32 v171, v83
	s_waitcnt lgkmcnt(0)
	v_mfma_f32_32x32x16_bf16 v[96:111], v[112:115], v[140:143], v[64:79]
	v_exp_f32_e32 v173, v84
	v_add_f32_e32 v80, v183, v152
	v_add_f32_e32 v80, 0, v80
	v_add_f32_e32 v81, v168, v167
	v_add_f32_e32 v80, v81, v80
	v_add_f32_e32 v81, v185, v169
	v_add_f32_e32 v80, v81, v80
	v_mfma_f32_32x32x16_bf16 v[112:127], v[188:191], v[140:143], v[64:79]
	ds_read_b128 v[188:191], v208 offset:45056
	ds_read_b128 v[192:195], v208 offset:40960
	v_add_f32_e32 v81, v166, v171
	v_exp_f32_e32 v154, v88
	v_exp_f32_e32 v155, v89
	v_add_f32_e32 v80, v81, v80
	v_add_f32_e32 v81, v186, v173
	v_add_f32_e32 v80, v81, v80
	s_waitcnt lgkmcnt(1)
	v_mfma_f32_32x32x16_bf16 v[112:127], v[188:191], v[136:139], v[112:127]
	v_exp_f32_e32 v156, v90
	v_exp_f32_e32 v157, v91
	v_exp_f32_e32 v158, v92
	v_exp_f32_e32 v159, v93
	v_exp_f32_e32 v160, v94
	v_exp_f32_e32 v161, v95
	s_waitcnt lgkmcnt(0)
	v_mfma_f32_32x32x16_bf16 v[96:111], v[192:195], v[136:139], v[96:111]
	ds_read_b128 v[188:191], v213 offset:45056
	ds_read_b128 v[192:195], v213 offset:40960
	s_waitcnt lgkmcnt(1)
	v_mfma_f32_32x32x16_bf16 v[112:127], v[188:191], v[132:135], v[112:127]
	s_waitcnt lgkmcnt(0)
	v_mfma_f32_32x32x16_bf16 v[96:111], v[192:195], v[132:135], v[96:111]
	ds_read_b128 v[188:191], v212 offset:45056
	ds_read_b128 v[192:195], v212 offset:40960
	s_waitcnt lgkmcnt(1)
	v_mfma_f32_32x32x16_bf16 v[112:127], v[188:191], v[128:131], v[112:127]
	v_exp_f32_e32 v188, v85
	v_exp_f32_e32 v189, v86
	v_exp_f32_e32 v190, v87
	v_add_f32_e32 v81, v172, v188
	v_add_f32_e32 v80, v81, v80
	v_add_f32_e32 v81, v187, v189
	v_add_f32_e32 v80, v81, v80
	v_add_f32_e32 v81, v170, v190
	v_add_f32_e32 v82, v81, v80
	v_pk_add_f32 v[80:81], v[176:177], v[154:155]
	s_waitcnt lgkmcnt(0)
	v_mfma_f32_32x32x16_bf16 v[96:111], v[192:195], v[128:131], v[96:111]
	v_add_f32_e32 v80, v80, v82
	v_add_f32_e32 v82, v81, v80
	v_add_f32_e64 v80, v174, v156
	v_add_f32_e64 v81, v175, v157
	v_add_f32_e32 v80, v80, v82
	v_add_f32_e32 v82, v81, v80
	v_pk_add_f32 v[80:81], v[180:181], v[158:159]
	s_nop 0
	v_add_f32_e32 v80, v80, v82
	v_add_f32_e32 v82, v81, v80
	v_pk_add_f32 v[80:81], v[178:179], v[160:161]
	s_nop 0
	v_add_f32_e32 v80, v80, v82
	v_add_f32_e32 v182, v81, v80
	v_cvt_pk_bf16_f32 v80, v183, v168
	v_cvt_pk_bf16_f32 v81, v185, v166
	v_cvt_pk_bf16_f32 v82, v186, v172
	v_cvt_pk_bf16_f32 v83, v187, v170
	v_cvt_pk_bf16_f32 v84, v176, v177
	v_cvt_pk_bf16_f32 v85, v174, v175
	v_cvt_pk_bf16_f32 v86, v180, v181
	v_cvt_pk_bf16_f32 v87, v178, v179
	v_cvt_pk_bf16_f32 v88, v152, v167
	v_cvt_pk_bf16_f32 v89, v169, v171
	v_cvt_pk_bf16_f32 v90, v173, v188
	v_cvt_pk_bf16_f32 v91, v189, v190
	v_cvt_pk_bf16_f32 v92, v154, v155
	v_cvt_pk_bf16_f32 v93, v156, v157
	v_cvt_pk_bf16_f32 v94, v158, v159
	v_cvt_pk_bf16_f32 v95, v160, v161
	v_mov_b32_e32 v184, v182
	v_permlane32_swap_b32_e32 v80, v82
	v_permlane32_swap_b32_e32 v81, v83
	v_permlane32_swap_b32_e32 v84, v86
	v_permlane32_swap_b32_e32 v85, v87
	v_permlane32_swap_b32_e32 v88, v90
	v_permlane32_swap_b32_e32 v89, v91
	v_permlane32_swap_b32_e32 v92, v94
	v_permlane32_swap_b32_e32 v93, v95
	v_permlane32_swap_b32_e32 v182, v184
	s_add_i32 s0, s9, 64
	s_and_b32 s0, s0, 0x7c0
	s_cmp_lt_u32 s16, 31
	s_cselect_b32 s1, s10, s18
	s_add_i32 s48, s1, s0
	v_lshl_add_u64 v[154:155], s[48:49], 0, v[144:145]
	v_mad_u64_u32 v[156:157], s[0:1], v154, s60, v[150:151]
	v_mad_i32_i24 v157, v155, s60, v157
	v_lshl_add_u64 v[154:155], s[48:49], 0, v[146:147]
	v_mov_b64_e32 v[166:167], s[70:71]
	global_load_dwordx4 v[236:239], v[156:157], off offset:3072
	v_mad_u64_u32 v[156:157], s[0:1], v154, s60, v[166:167]
	v_mad_i32_i24 v157, v155, s60, v157
	s_mov_b32 s91, s49
	v_lshl_add_u64 v[154:155], v[156:157], 0, s[90:91]
	v_lshl_add_u64 v[154:155], v[154:155], 0, v[148:149]
	v_add_co_u32_e32 v156, vcc, s58, v154
	s_nop 1
	v_addc_co_u32_e32 v157, vcc, 0, v155, vcc
	global_load_dwordx4 v[244:247], v[154:155], off
	global_load_dwordx4 v[248:251], v[156:157], off
	ds_read_b64_tr_b16 v[168:169], v206 offset:0
	ds_read_b64_tr_b16 v[170:171], v206 offset:0x800
	ds_read_b64_tr_b16 v[172:173], v206 offset:0x1000
	ds_read_b64_tr_b16 v[174:175], v206 offset:0x1800
	ds_read_b64_tr_b16 v[176:177], v206 offset:0x2000
	ds_read_b64_tr_b16 v[178:179], v206 offset:0x2800
	ds_read_b64_tr_b16 v[190:191], v206 offset:0x3000
	ds_read_b64_tr_b16 v[192:193], v206 offset:0x3800
	s_waitcnt lgkmcnt(0)
	s_nop 0
	v_mfma_f32_32x32x16_bf16 v[48:63], v[80:83], v[168:171], v[48:63]
	v_exp_f32_e32 v154, v96
	v_exp_f32_e32 v168, v97
	ds_read_b64_tr_b16 v[96:97], v206 offset:0x200
	v_exp_f32_e32 v155, v98
	v_exp_f32_e32 v170, v99
	ds_read_b64_tr_b16 v[98:99], v206 offset:0xa00
	v_mfma_f32_32x32x16_bf16 v[48:63], v[84:87], v[172:175], v[48:63]
	ds_read_b64_tr_b16 v[172:173], v206 offset:0x1200
	ds_read_b64_tr_b16 v[174:175], v206 offset:0x1a00
	v_mfma_f32_32x32x16_bf16 v[48:63], v[88:91], v[176:179], v[48:63]
	ds_read_b64_tr_b16 v[176:177], v206 offset:0x2200
	ds_read_b64_tr_b16 v[178:179], v206 offset:0x2a00
	v_mfma_f32_32x32x16_bf16 v[48:63], v[92:95], v[190:193], v[48:63]
	ds_read_b64_tr_b16 v[190:191], v206 offset:0x3200
	ds_read_b64_tr_b16 v[192:193], v206 offset:0x3a00
	s_waitcnt lgkmcnt(0)
	v_mfma_f32_32x32x16_bf16 v[32:47], v[80:83], v[96:99], v[32:47]
	s_waitcnt vmcnt(3)
	ds_write_b128 v209, v[162:165] offset:32768
	ds_write_b128 v210, v[224:227]
	ds_write_b128 v211, v[232:235]
	ds_read_b64_tr_b16 v[96:97], v206 offset:0x400
	ds_read_b64_tr_b16 v[98:99], v206 offset:0xc00
	v_exp_f32_e32 v156, v100
	v_exp_f32_e32 v157, v102
	v_mfma_f32_32x32x16_bf16 v[32:47], v[84:87], v[172:175], v[32:47]
	v_exp_f32_e32 v172, v101
	ds_read_b64_tr_b16 v[100:101], v206 offset:0x1400
	v_exp_f32_e32 v174, v103
	ds_read_b64_tr_b16 v[102:103], v206 offset:0x1c00
	v_mfma_f32_32x32x16_bf16 v[32:47], v[88:91], v[176:179], v[32:47]
	ds_read_b64_tr_b16 v[176:177], v206 offset:0x2400
	ds_read_b64_tr_b16 v[178:179], v206 offset:0x2c00
	v_mfma_f32_32x32x16_bf16 v[32:47], v[92:95], v[190:193], v[32:47]
	ds_read_b64_tr_b16 v[190:191], v206 offset:0x3400
	ds_read_b64_tr_b16 v[192:193], v206 offset:0x3c00
	v_xor_b32_e32 v207, 0x10000, v207
	v_xor_b32_e32 v208, 0x10000, v208
	v_xor_b32_e32 v213, 0x10000, v213
	v_xor_b32_e32 v212, 0x10000, v212
	s_waitcnt lgkmcnt(0)
	v_mfma_f32_32x32x16_bf16 v[16:31], v[80:83], v[96:99], v[16:31]
	ds_read_b64_tr_b16 v[96:97], v206 offset:0x600
	ds_read_b64_tr_b16 v[98:99], v206 offset:0xe00
	v_exp_f32_e32 v158, v104
	v_exp_f32_e32 v159, v106
	v_mfma_f32_32x32x16_bf16 v[16:31], v[84:87], v[100:103], v[16:31]
	ds_read_b64_tr_b16 v[100:101], v206 offset:0x1600
	ds_read_b64_tr_b16 v[102:103], v206 offset:0x1e00
	v_mfma_f32_32x32x16_bf16 v[16:31], v[88:91], v[176:179], v[16:31]
	v_exp_f32_e32 v176, v105
	ds_read_b64_tr_b16 v[104:105], v206 offset:0x2600
	v_exp_f32_e32 v178, v107
	ds_read_b64_tr_b16 v[106:107], v206 offset:0x2e00
	ds_read_b64_tr_b16 v[220:221], v206 offset:0x3600
	ds_read_b64_tr_b16 v[222:223], v206 offset:0x3e00
	s_waitcnt lgkmcnt(0)
	v_mfma_f32_32x32x16_bf16 v[16:31], v[92:95], v[190:193], v[16:31]
	v_mfma_f32_32x32x16_bf16 v[0:15], v[80:83], v[96:99], v[0:15]
	v_exp_f32_e32 v160, v108
	v_exp_f32_e32 v192, v109
	v_exp_f32_e32 v161, v110
	v_exp_f32_e32 v194, v111
	v_mfma_f32_32x32x16_bf16 v[0:15], v[84:87], v[100:103], v[0:15]
	s_waitcnt lgkmcnt(0)
	s_barrier
	v_mfma_f32_32x32x16_bf16 v[0:15], v[88:91], v[104:107], v[0:15]
	v_mfma_f32_32x32x16_bf16 v[0:15], v[92:95], v[220:223], v[0:15]
	ds_read_b128 v[186:189], v207 offset:36864
	ds_read_b128 v[80:83], v207 offset:32768
	v_exp_f32_e32 v215, v112
	v_exp_f32_e32 v152, v113
	v_exp_f32_e32 v216, v114
	v_exp_f32_e32 v217, v116
	s_waitcnt lgkmcnt(0)
	v_mfma_f32_32x32x16_bf16 v[96:111], v[80:83], v[140:143], v[64:79]
	v_add_f32_e32 v169, v154, v215
	v_add_f32_e64 v112, v168, v152
	v_add_f32_e64 v113, v169, v153
	v_add_f32_e32 v171, v155, v216
	v_pk_add_f32 v[112:113], v[112:113], v[112:113] op_sel_hi:[0,1]
	v_exp_f32_e32 v218, v118
	v_exp_f32_e32 v200, v119
	v_add_f32_e32 v173, v156, v217
	v_mfma_f32_32x32x16_bf16 v[80:95], v[186:189], v[140:143], v[64:79]
	ds_read_b128 v[186:189], v208 offset:36864
	ds_read_b128 v[196:199], v208 offset:32768
	v_exp_f32_e32 v219, v120
	v_exp_f32_e32 v180, v121
	v_add_f32_e32 v175, v157, v218
	v_exp_f32_e32 v220, v122
	v_add_f32_e32 v177, v158, v219
	v_exp_f32_e32 v221, v124
	s_waitcnt lgkmcnt(0)
	v_mfma_f32_32x32x16_bf16 v[96:111], v[196:199], v[136:139], v[96:111]
	v_add_f32_e32 v179, v159, v220
	v_exp_f32_e32 v222, v126
	v_exp_f32_e32 v190, v127
	v_add_f32_e32 v193, v160, v221
	v_add_f32_e32 v195, v161, v222
	v_mfma_f32_32x32x16_bf16 v[80:95], v[186:189], v[136:139], v[80:95]
	ds_read_b128 v[186:189], v213 offset:36864
	ds_read_b128 v[196:199], v213 offset:32768
	s_waitcnt lgkmcnt(0)
	v_mfma_f32_32x32x16_bf16 v[96:111], v[196:199], v[132:135], v[96:111]
	v_mfma_f32_32x32x16_bf16 v[80:95], v[186:189], v[132:135], v[80:95]
	ds_read_b128 v[186:189], v212 offset:36864
	ds_read_b128 v[196:199], v212 offset:32768
	s_waitcnt lgkmcnt(0)
	v_mfma_f32_32x32x16_bf16 v[96:111], v[196:199], v[128:131], v[96:111]
	v_exp_f32_e32 v196, v115
	v_exp_f32_e32 v198, v117
	v_mov_b32_e32 v197, v113
	v_pk_add_f32 v[112:113], v[170:171], v[196:197]
	s_nop 0
	v_pk_add_f32 v[112:113], v[112:113], v[112:113] op_sel_hi:[0,1]
	v_mov_b32_e32 v199, v113
	v_pk_add_f32 v[112:113], v[172:173], v[198:199]
	v_mfma_f32_32x32x16_bf16 v[80:95], v[186:189], v[128:131], v[80:95]
	v_pk_add_f32 v[112:113], v[112:113], v[112:113] op_sel_hi:[0,1]
	v_mov_b32_e32 v201, v113
	v_pk_add_f32 v[112:113], v[174:175], v[200:201]
	v_exp_f32_e32 v186, v123
	v_pk_add_f32 v[112:113], v[112:113], v[112:113] op_sel_hi:[0,1]
	v_mov_b32_e32 v181, v113
	v_pk_add_f32 v[112:113], v[176:177], v[180:181]
	v_exp_f32_e32 v188, v125
	v_pk_add_f32 v[112:113], v[112:113], v[112:113] op_sel_hi:[0,1]
	v_mov_b32_e32 v187, v113
	v_pk_add_f32 v[112:113], v[178:179], v[186:187]
	s_nop 0
	v_pk_add_f32 v[112:113], v[112:113], v[112:113] op_sel_hi:[0,1]
	v_mov_b32_e32 v189, v113
	v_pk_add_f32 v[112:113], v[192:193], v[188:189]
	s_nop 0
	v_pk_add_f32 v[112:113], v[112:113], v[112:113] op_sel_hi:[0,1]
	v_mov_b32_e32 v191, v113
	v_pk_add_f32 v[112:113], v[194:195], v[190:191]
	s_nop 0
	v_pk_add_f32 v[112:113], v[112:113], v[112:113] op_sel:[0,1] op_sel_hi:[1,0]
	s_nop 0
	v_mov_b32_e32 v185, v112
	s_nop 1
	v_permlane32_swap_b32_e32 v112, v185
	v_mov_b32_e32 v183, v112
	v_pk_add_f32 v[112:113], v[182:183], v[184:185]
	s_nop 0
	v_cmp_ngt_f32_e32 vcc, s59, v113
	v_cmp_ngt_f32_e64 s[0:1], s59, v112
	v_fma_f32 v114, v204, v214, v112
	s_or_b64 s[0:1], s[0:1], vcc
	v_add_f32_e32 v204, v114, v113
	s_or_b64 s[14:15], s[14:15], s[0:1]
	v_cvt_pk_bf16_f32 v112, v154, v168
	v_cvt_pk_bf16_f32 v113, v155, v170
	v_cvt_pk_bf16_f32 v114, v156, v172
	v_cvt_pk_bf16_f32 v115, v157, v174
	v_cvt_pk_bf16_f32 v116, v158, v176
	v_cvt_pk_bf16_f32 v117, v159, v178
	v_cvt_pk_bf16_f32 v118, v160, v192
	v_cvt_pk_bf16_f32 v119, v161, v194
	v_cvt_pk_bf16_f32 v120, v215, v152
	v_cvt_pk_bf16_f32 v121, v216, v196
	v_cvt_pk_bf16_f32 v122, v217, v198
	v_cvt_pk_bf16_f32 v123, v218, v200
	v_cvt_pk_bf16_f32 v124, v219, v180
	v_cvt_pk_bf16_f32 v125, v220, v186
	v_cvt_pk_bf16_f32 v126, v221, v188
	v_cvt_pk_bf16_f32 v127, v222, v190
	s_nop 0
	v_permlane32_swap_b32_e32 v112, v114
	v_permlane32_swap_b32_e32 v113, v115
	v_permlane32_swap_b32_e32 v116, v118
	v_permlane32_swap_b32_e32 v117, v119
	v_permlane32_swap_b32_e32 v120, v122
	v_permlane32_swap_b32_e32 v121, v123
	v_permlane32_swap_b32_e32 v124, v126
	v_permlane32_swap_b32_e32 v125, v127
	s_add_i32 s0, s16, -1
	s_cmp_lt_u32 s16, 30
	s_cselect_b32 s1, 0, 0xffffffe0
	s_cselect_b32 s17, s10, s18
	s_add_i32 s1, s1, s16
	s_lshl_b32 s1, s1, 6
	s_add_i32 s1, s1, s17
	s_add_i32 s48, s1, 0x80
	v_lshl_add_u64 v[154:155], s[48:49], 0, v[144:145]
	v_mad_u64_u32 v[156:157], s[22:23], v154, s60, v[150:151]
	v_mad_i32_i24 v157, v155, s60, v157
	v_lshl_add_u64 v[154:155], s[48:49], 0, v[146:147]
	global_load_dwordx4 v[162:165], v[156:157], off offset:3072
	v_mad_u64_u32 v[156:157], s[22:23], v154, s60, v[166:167]
	v_mad_i32_i24 v157, v155, s60, v157
	v_lshl_add_u64 v[154:155], v[156:157], 0, s[90:91]
	v_lshl_add_u64 v[154:155], v[154:155], 0, v[148:149]
	v_add_co_u32_e32 v156, vcc, s58, v154
	s_nop 1
	v_addc_co_u32_e32 v157, vcc, 0, v155, vcc
	global_load_dwordx4 v[224:227], v[154:155], off
	global_load_dwordx4 v[232:235], v[156:157], off
	ds_read_b64_tr_b16 v[166:167], v205 offset:0
	ds_read_b64_tr_b16 v[168:169], v205 offset:0x800
	ds_read_b64_tr_b16 v[170:171], v205 offset:0x1000
	ds_read_b64_tr_b16 v[172:173], v205 offset:0x1800
	ds_read_b64_tr_b16 v[174:175], v205 offset:0x2000
	ds_read_b64_tr_b16 v[176:177], v205 offset:0x2800
	ds_read_b64_tr_b16 v[178:179], v205 offset:0x3000
	ds_read_b64_tr_b16 v[180:181], v205 offset:0x3800
	s_waitcnt lgkmcnt(0)
	s_nop 0
	v_mfma_f32_32x32x16_bf16 v[48:63], v[112:115], v[166:169], v[48:63]
	v_exp_f32_e32 v183, v96
	v_exp_f32_e32 v168, v97
	ds_read_b64_tr_b16 v[96:97], v205 offset:0x200
	v_exp_f32_e32 v185, v98
	v_exp_f32_e32 v166, v99
	ds_read_b64_tr_b16 v[98:99], v205 offset:0xa00
	v_mfma_f32_32x32x16_bf16 v[48:63], v[116:119], v[170:173], v[48:63]
	ds_read_b64_tr_b16 v[170:171], v205 offset:0x1200
	ds_read_b64_tr_b16 v[172:173], v205 offset:0x1a00
	v_mfma_f32_32x32x16_bf16 v[48:63], v[120:123], v[174:177], v[48:63]
	ds_read_b64_tr_b16 v[174:175], v205 offset:0x2200
	ds_read_b64_tr_b16 v[176:177], v205 offset:0x2a00
	v_mfma_f32_32x32x16_bf16 v[48:63], v[124:127], v[178:181], v[48:63]
	ds_read_b64_tr_b16 v[178:179], v205 offset:0x3200
	ds_read_b64_tr_b16 v[180:181], v205 offset:0x3a00
	s_waitcnt lgkmcnt(0)
	v_mfma_f32_32x32x16_bf16 v[32:47], v[112:115], v[96:99], v[32:47]
	s_waitcnt vmcnt(3)
	ds_write_b128 v209, v[236:239] offset:40960
	ds_write_b128 v210, v[244:247] offset:16384
	ds_write_b128 v211, v[248:251] offset:16384
	ds_read_b64_tr_b16 v[96:97], v205 offset:0x400
	ds_read_b64_tr_b16 v[98:99], v205 offset:0xc00
	v_exp_f32_e32 v186, v100
	v_exp_f32_e32 v187, v102
	v_mfma_f32_32x32x16_bf16 v[32:47], v[116:119], v[170:173], v[32:47]
	v_exp_f32_e32 v172, v101
	ds_read_b64_tr_b16 v[100:101], v205 offset:0x1400
	v_exp_f32_e32 v170, v103
	ds_read_b64_tr_b16 v[102:103], v205 offset:0x1c00
	v_mfma_f32_32x32x16_bf16 v[32:47], v[120:123], v[174:177], v[32:47]
	ds_read_b64_tr_b16 v[174:175], v205 offset:0x2400
	ds_read_b64_tr_b16 v[176:177], v205 offset:0x2c00
	v_mfma_f32_32x32x16_bf16 v[32:47], v[124:127], v[178:181], v[32:47]
	ds_read_b64_tr_b16 v[178:179], v205 offset:0x3400
	ds_read_b64_tr_b16 v[180:181], v205 offset:0x3c00
	v_xor_b32_e32 v206, 0x10000, v206
	s_waitcnt lgkmcnt(0)
	v_mfma_f32_32x32x16_bf16 v[16:31], v[112:115], v[96:99], v[16:31]
	ds_read_b64_tr_b16 v[96:97], v205 offset:0x600
	ds_read_b64_tr_b16 v[98:99], v205 offset:0xe00
	v_mfma_f32_32x32x16_bf16 v[16:31], v[116:119], v[100:103], v[16:31]
	ds_read_b64_tr_b16 v[100:101], v205 offset:0x1600
	ds_read_b64_tr_b16 v[102:103], v205 offset:0x1e00
	v_mfma_f32_32x32x16_bf16 v[16:31], v[120:123], v[174:177], v[16:31]
	v_exp_f32_e32 v176, v104
	v_exp_f32_e32 v177, v105
	ds_read_b64_tr_b16 v[104:105], v205 offset:0x2600
	v_exp_f32_e32 v174, v106
	v_exp_f32_e32 v175, v107
	ds_read_b64_tr_b16 v[106:107], v205 offset:0x2e00
	ds_read_b64_tr_b16 v[214:215], v205 offset:0x3600
	v_mfma_f32_32x32x16_bf16 v[16:31], v[124:127], v[178:181], v[16:31]
	ds_read_b64_tr_b16 v[216:217], v205 offset:0x3e00
	s_waitcnt lgkmcnt(0)
	v_mfma_f32_32x32x16_bf16 v[0:15], v[112:115], v[96:99], v[0:15]
	v_exp_f32_e32 v180, v108
	v_exp_f32_e32 v181, v109
	v_exp_f32_e32 v178, v110
	v_exp_f32_e32 v179, v111
	s_andn2_b64 s[2:3], s[2:3], exec
	s_and_b64 s[22:23], s[14:15], exec
	s_addk_i32 s9, 0x80
	v_mfma_f32_32x32x16_bf16 v[0:15], v[116:119], v[100:103], v[0:15]
	s_add_i32 s16, s16, 2
	s_or_b64 s[2:3], s[2:3], s[22:23]
	s_cmp_gt_u32 s0, 32
	v_xor_b32_e32 v205, 0x10000, v205
	v_xor_b32_e32 v209, 0x10000, v209
	v_xor_b32_e32 v210, 0x10000, v210
	v_xor_b32_e32 v211, 0x10000, v211
	v_mfma_f32_32x32x16_bf16 v[0:15], v[120:123], v[104:107], v[0:15]
	s_waitcnt lgkmcnt(0)
	s_barrier
	v_mfma_f32_32x32x16_bf16 v[0:15], v[124:127], v[214:217], v[0:15]
	v_mov_b32_e32 v214, 1.0
	s_cbranch_scc0 .LBB0_797
	v_mov_b32_e32 v239, s100
	ds_read_b128 v[112:115], v207 offset:45056
	ds_read_b128 v[116:119], v207 offset:40960
	v_exp_f32_e32 v152, v81
	v_exp_f32_e32 v124, v84
	v_exp_f32_e32 v84, v85
	v_exp_f32_e32 v125, v86
	s_waitcnt lgkmcnt(0)
	v_mfma_f32_32x32x16_bf16 v[96:111], v[116:119], v[140:143], v[64:79]
	v_exp_f32_e32 v86, v87
	v_add_f32_e32 v173, v186, v124
	v_exp_f32_e32 v126, v88
	v_add_f32_e32 v171, v187, v125
	v_exp_f32_e32 v127, v90
	v_exp_f32_e32 v120, v93
	v_exp_f32_e32 v122, v95
	v_mfma_f32_32x32x16_bf16 v[64:79], v[112:115], v[140:143], v[64:79]
	ds_read_b128 v[112:115], v208 offset:45056
	ds_read_b128 v[116:119], v208 offset:40960
	s_waitcnt lgkmcnt(1)
	v_mfma_f32_32x32x16_bf16 v[64:79], v[112:115], v[136:139], v[64:79]
	s_waitcnt lgkmcnt(0)
	v_mfma_f32_32x32x16_bf16 v[96:111], v[116:119], v[136:139], v[96:111]
	ds_read_b128 v[112:115], v213 offset:45056
	ds_read_b128 v[116:119], v213 offset:40960
	s_waitcnt lgkmcnt(1)
	v_mfma_f32_32x32x16_bf16 v[64:79], v[112:115], v[132:135], v[64:79]
	s_waitcnt lgkmcnt(0)
	v_mfma_f32_32x32x16_bf16 v[96:111], v[116:119], v[132:135], v[96:111]
	ds_read_b128 v[112:115], v212 offset:45056
	ds_read_b128 v[116:119], v212 offset:40960
	v_cvt_pk_bf16_f32 v88, v183, v168
	s_waitcnt lgkmcnt(1)
	v_mfma_f32_32x32x16_bf16 v[64:79], v[112:115], v[128:131], v[64:79]
	v_exp_f32_e32 v112, v80
	v_exp_f32_e32 v113, v82
	v_exp_f32_e32 v114, v83
	v_add_f32_e32 v83, v176, v126
	v_add_f32_e32 v169, v183, v112
	v_pk_add_f32 v[80:81], v[168:169], v[152:153]
	v_add_f32_e32 v167, v185, v113
	v_pk_add_f32 v[80:81], v[80:81], v[80:81] op_sel_hi:[0,1]
	v_mov_b32_e32 v115, v81
	v_pk_add_f32 v[80:81], v[166:167], v[114:115]
	s_waitcnt lgkmcnt(0)
	v_mfma_f32_32x32x16_bf16 v[96:111], v[116:119], v[128:131], v[96:111]
	v_pk_add_f32 v[80:81], v[80:81], v[80:81] op_sel_hi:[0,1]
	v_mov_b32_e32 v85, v81
	v_pk_add_f32 v[80:81], v[172:173], v[84:85]
	v_exp_f32_e32 v116, v89
	v_pk_add_f32 v[80:81], v[80:81], v[80:81] op_sel_hi:[0,1]
	v_mov_b32_e32 v87, v81
	v_pk_add_f32 v[80:81], v[170:171], v[86:87]
	v_exp_f32_e32 v118, v91
	v_pk_add_f32 v[80:81], v[80:81], v[80:81] op_sel_hi:[0,1]
	v_mov_b32_e32 v82, v177
	v_mov_b32_e32 v117, v81
	v_pk_add_f32 v[80:81], v[82:83], v[116:117]
	v_exp_f32_e32 v128, v92
	v_pk_add_f32 v[80:81], v[80:81], v[80:81] op_sel_hi:[0,1]
	v_add_f32_e32 v83, v174, v127
	v_mov_b32_e32 v82, v175
	v_mov_b32_e32 v119, v81
	v_pk_add_f32 v[80:81], v[82:83], v[118:119]
	v_exp_f32_e32 v129, v94
	v_pk_add_f32 v[80:81], v[80:81], v[80:81] op_sel_hi:[0,1]
	v_add_f32_e32 v83, v180, v128
	v_mov_b32_e32 v82, v181
	v_mov_b32_e32 v121, v81
	v_pk_add_f32 v[80:81], v[82:83], v[120:121]
	v_add_f32_e32 v83, v178, v129
	v_pk_add_f32 v[80:81], v[80:81], v[80:81] op_sel_hi:[0,1]
	v_mov_b32_e32 v82, v179
	v_mov_b32_e32 v123, v81
	v_pk_add_f32 v[80:81], v[82:83], v[122:123]
	v_cvt_pk_bf16_f32 v89, v185, v166
	v_cvt_pk_bf16_f32 v90, v186, v172
	v_cvt_pk_bf16_f32 v91, v187, v170
	v_cvt_pk_bf16_f32 v92, v176, v177
	v_cvt_pk_bf16_f32 v93, v174, v175
	s_nop 0
	v_pk_add_f32 v[80:81], v[80:81], v[80:81] op_sel:[0,1] op_sel_hi:[1,0]
	v_cvt_pk_bf16_f32 v94, v180, v181
	v_cvt_pk_bf16_f32 v95, v178, v179
	v_cvt_pk_bf16_f32 v112, v112, v152
	v_cvt_pk_bf16_f32 v113, v113, v114
	v_cvt_pk_bf16_f32 v114, v124, v84
	s_nop 0
	v_mov_b32_e32 v82, v80
	v_cvt_pk_bf16_f32 v115, v125, v86
	v_cvt_pk_bf16_f32 v116, v126, v116
	v_cvt_pk_bf16_f32 v117, v127, v118
	v_cvt_pk_bf16_f32 v118, v128, v120
	v_cvt_pk_bf16_f32 v119, v129, v122
	s_nop 1
	v_permlane32_swap_b32_e32 v80, v82
	v_permlane32_swap_b32_e32 v88, v90
	v_permlane32_swap_b32_e32 v89, v91
	v_permlane32_swap_b32_e32 v92, v94
	v_permlane32_swap_b32_e32 v93, v95
	v_permlane32_swap_b32_e32 v112, v114
	v_permlane32_swap_b32_e32 v113, v115
	v_permlane32_swap_b32_e32 v116, v118
	v_permlane32_swap_b32_e32 v117, v119
	ds_read_b64_tr_b16 v[84:85], v206 offset:0
	ds_read_b64_tr_b16 v[86:87], v206 offset:0x800
	ds_read_b64_tr_b16 v[120:121], v206 offset:0x1000
	ds_read_b64_tr_b16 v[122:123], v206 offset:0x1800
	ds_read_b64_tr_b16 v[124:125], v206 offset:0x2000
	ds_read_b64_tr_b16 v[126:127], v206 offset:0x2800
	ds_read_b64_tr_b16 v[128:129], v206 offset:0x3000
	ds_read_b64_tr_b16 v[130:131], v206 offset:0x3800
	s_waitcnt lgkmcnt(0)
	s_nop 0
	v_mfma_f32_32x32x16_bf16 v[48:63], v[88:91], v[84:87], v[48:63]
	v_exp_f32_e32 v132, v96
	v_exp_f32_e32 v84, v97
	ds_read_b64_tr_b16 v[96:97], v206 offset:0x200
	v_exp_f32_e32 v133, v98
	v_exp_f32_e32 v86, v99
	ds_read_b64_tr_b16 v[98:99], v206 offset:0xa00
	v_mfma_f32_32x32x16_bf16 v[48:63], v[92:95], v[120:123], v[48:63]
	ds_read_b64_tr_b16 v[120:121], v206 offset:0x1200
	ds_read_b64_tr_b16 v[122:123], v206 offset:0x1a00
	v_mfma_f32_32x32x16_bf16 v[48:63], v[112:115], v[124:127], v[48:63]
	ds_read_b64_tr_b16 v[124:125], v206 offset:0x2200
	ds_read_b64_tr_b16 v[126:127], v206 offset:0x2a00
	v_mfma_f32_32x32x16_bf16 v[48:63], v[116:119], v[128:131], v[48:63]
	ds_read_b64_tr_b16 v[128:129], v206 offset:0x3200
	ds_read_b64_tr_b16 v[130:131], v206 offset:0x3a00
	s_waitcnt lgkmcnt(0)
	v_mfma_f32_32x32x16_bf16 v[32:47], v[88:91], v[96:99], v[32:47]
	ds_read_b64_tr_b16 v[96:97], v206 offset:0x400
	ds_read_b64_tr_b16 v[98:99], v206 offset:0xc00
	v_exp_f32_e32 v134, v100
	v_exp_f32_e32 v135, v102
	v_mfma_f32_32x32x16_bf16 v[32:47], v[92:95], v[120:123], v[32:47]
	v_mfma_f32_32x32x16_bf16 v[32:47], v[112:115], v[124:127], v[32:47]
	v_mfma_f32_32x32x16_bf16 v[32:47], v[116:119], v[128:131], v[32:47]
	v_exp_f32_e32 v128, v101
	ds_read_b64_tr_b16 v[100:101], v206 offset:0x1400
	v_exp_f32_e32 v130, v103
	ds_read_b64_tr_b16 v[102:103], v206 offset:0x1c00
	ds_read_b64_tr_b16 v[120:121], v206 offset:0x2400
	ds_read_b64_tr_b16 v[122:123], v206 offset:0x2c00
	ds_read_b64_tr_b16 v[124:125], v206 offset:0x3400
	ds_read_b64_tr_b16 v[126:127], v206 offset:0x3c00
	s_waitcnt lgkmcnt(0)
	v_mfma_f32_32x32x16_bf16 v[16:31], v[88:91], v[96:99], v[16:31]
	ds_read_b64_tr_b16 v[96:97], v206 offset:0x600
	ds_read_b64_tr_b16 v[98:99], v206 offset:0xe00
	v_exp_f32_e32 v136, v104
	v_exp_f32_e32 v137, v106
	v_mfma_f32_32x32x16_bf16 v[16:31], v[92:95], v[100:103], v[16:31]
	ds_read_b64_tr_b16 v[100:101], v206 offset:0x1600
	ds_read_b64_tr_b16 v[102:103], v206 offset:0x1e00
	v_mfma_f32_32x32x16_bf16 v[16:31], v[112:115], v[120:123], v[16:31]
	v_mfma_f32_32x32x16_bf16 v[16:31], v[116:119], v[124:127], v[16:31]
	v_exp_f32_e32 v124, v105
	ds_read_b64_tr_b16 v[104:105], v206 offset:0x2600
	v_exp_f32_e32 v126, v107
	ds_read_b64_tr_b16 v[106:107], v206 offset:0x2e00
	ds_read_b64_tr_b16 v[120:121], v206 offset:0x3600
	ds_read_b64_tr_b16 v[122:123], v206 offset:0x3e00
	s_waitcnt lgkmcnt(0)
	v_mfma_f32_32x32x16_bf16 v[0:15], v[88:91], v[96:99], v[0:15]
	v_exp_f32_e32 v152, v65
	v_exp_f32_e32 v88, v109
	v_exp_f32_e32 v109, v66
	v_exp_f32_e32 v90, v111
	v_exp_f32_e32 v111, v70
	v_exp_f32_e32 v96, v71
	v_add_f32_e32 v87, v133, v109
	v_mfma_f32_32x32x16_bf16 v[0:15], v[92:95], v[100:103], v[0:15]
	v_exp_f32_e32 v92, v67
	v_exp_f32_e32 v94, v69
	v_exp_f32_e32 v98, v73
	v_add_f32_e32 v131, v135, v111
	v_exp_f32_e32 v100, v75
	v_exp_f32_e32 v102, v77
	v_cvt_pk_bf16_f32 v66, v132, v84
	v_mfma_f32_32x32x16_bf16 v[0:15], v[112:115], v[104:107], v[0:15]
	v_exp_f32_e32 v106, v108
	v_exp_f32_e32 v108, v64
	v_exp_f32_e32 v107, v110
	v_exp_f32_e32 v110, v68
	v_exp_f32_e32 v112, v72
	v_add_f32_e32 v85, v132, v108
	v_pk_add_f32 v[64:65], v[84:85], v[152:153]
	v_add_f32_e32 v129, v134, v110
	v_pk_add_f32 v[64:65], v[64:65], v[64:65] op_sel_hi:[0,1]
	v_mov_b32_e32 v93, v65
	v_pk_add_f32 v[64:65], v[86:87], v[92:93]
	v_exp_f32_e32 v113, v74
	v_pk_add_f32 v[64:65], v[64:65], v[64:65] op_sel_hi:[0,1]
	v_mov_b32_e32 v95, v65
	v_pk_add_f32 v[64:65], v[128:129], v[94:95]
	v_add_f32_e32 v125, v136, v112
	v_pk_add_f32 v[64:65], v[64:65], v[64:65] op_sel_hi:[0,1]
	v_mov_b32_e32 v97, v65
	v_pk_add_f32 v[64:65], v[130:131], v[96:97]
	v_exp_f32_e32 v114, v76
	v_pk_add_f32 v[64:65], v[64:65], v[64:65] op_sel_hi:[0,1]
	v_mov_b32_e32 v99, v65
	v_pk_add_f32 v[64:65], v[124:125], v[98:99]
	v_add_f32_e32 v127, v137, v113
	v_pk_add_f32 v[64:65], v[64:65], v[64:65] op_sel_hi:[0,1]
	v_mov_b32_e32 v101, v65
	v_pk_add_f32 v[64:65], v[126:127], v[100:101]
	v_exp_f32_e32 v115, v78
	v_pk_add_f32 v[64:65], v[64:65], v[64:65] op_sel_hi:[0,1]
	v_exp_f32_e32 v104, v79
	v_add_f32_e32 v89, v106, v114
	v_mov_b32_e32 v103, v65
	v_pk_add_f32 v[64:65], v[88:89], v[102:103]
	v_add_f32_e32 v91, v107, v115
	v_pk_add_f32 v[64:65], v[64:65], v[64:65] op_sel_hi:[0,1]
	v_mov_b32_e32 v105, v65
	v_pk_add_f32 v[64:65], v[90:91], v[104:105]
	v_mfma_f32_32x32x16_bf16 v[0:15], v[116:119], v[120:123], v[0:15]
	v_pk_add_f32 v[64:65], v[64:65], v[64:65] op_sel:[0,1] op_sel_hi:[1,0]
	v_cvt_pk_bf16_f32 v67, v133, v86
	v_cvt_pk_bf16_f32 v68, v134, v128
	v_cvt_pk_bf16_f32 v69, v135, v130
	v_cvt_pk_bf16_f32 v70, v136, v124
	v_cvt_pk_bf16_f32 v71, v137, v126
	s_nop 0
	v_mov_b32_e32 v83, v64
	s_nop 1
	v_permlane32_swap_b32_e32 v64, v83
	v_mov_b32_e32 v81, v64
	v_pk_add_f32 v[64:65], v[80:81], v[82:83]
	v_cvt_pk_bf16_f32 v72, v106, v88
	v_cvt_pk_bf16_f32 v73, v107, v90
	v_cvt_pk_bf16_f32 v74, v108, v152
	v_cvt_pk_bf16_f32 v75, v109, v92
	v_cvt_pk_bf16_f32 v76, v110, v94
	s_nop 0
	v_cmp_ngt_f32_e32 vcc, s59, v65
	v_cmp_ngt_f32_e64 s[0:1], s59, v64
	s_or_b64 s[0:1], s[0:1], vcc
	s_or_b64 s[0:1], s[2:3], s[0:1]
	v_cvt_pk_bf16_f32 v77, v111, v96
	v_cvt_pk_bf16_f32 v78, v112, v98
	v_cvt_pk_bf16_f32 v79, v113, v100
	v_cvt_pk_bf16_f32 v80, v114, v102
	v_cvt_pk_bf16_f32 v81, v115, v104
	v_permlane32_swap_b32_e32 v66, v68
	v_permlane32_swap_b32_e32 v67, v69
	v_permlane32_swap_b32_e32 v70, v72
	v_permlane32_swap_b32_e32 v71, v73
	v_permlane32_swap_b32_e32 v74, v76
	v_permlane32_swap_b32_e32 v75, v77
	v_permlane32_swap_b32_e32 v78, v80
	v_permlane32_swap_b32_e32 v79, v81
	ds_read_b64_tr_b16 v[82:83], v205 offset:0
	ds_read_b64_tr_b16 v[84:85], v205 offset:0x800
	ds_read_b64_tr_b16 v[86:87], v205 offset:0x1000
	ds_read_b64_tr_b16 v[88:89], v205 offset:0x1800
	ds_read_b64_tr_b16 v[90:91], v205 offset:0x2000
	ds_read_b64_tr_b16 v[92:93], v205 offset:0x2800
	ds_read_b64_tr_b16 v[94:95], v205 offset:0x3000
	ds_read_b64_tr_b16 v[96:97], v205 offset:0x3800
	s_waitcnt lgkmcnt(0)
	s_nop 0
	v_mfma_f32_32x32x16_bf16 v[48:63], v[66:69], v[82:85], v[48:63]
	ds_read_b64_tr_b16 v[82:83], v205 offset:0x200
	ds_read_b64_tr_b16 v[84:85], v205 offset:0xa00
	v_mfma_f32_32x32x16_bf16 v[48:63], v[70:73], v[86:89], v[48:63]
	ds_read_b64_tr_b16 v[86:87], v205 offset:0x1200
	ds_read_b64_tr_b16 v[88:89], v205 offset:0x1a00
	v_mfma_f32_32x32x16_bf16 v[48:63], v[74:77], v[90:93], v[48:63]
	ds_read_b64_tr_b16 v[90:91], v205 offset:0x2200
	ds_read_b64_tr_b16 v[92:93], v205 offset:0x2a00
	v_mfma_f32_32x32x16_bf16 v[48:63], v[78:81], v[94:97], v[48:63]
	ds_read_b64_tr_b16 v[94:95], v205 offset:0x3200
	ds_read_b64_tr_b16 v[96:97], v205 offset:0x3a00
	s_waitcnt lgkmcnt(0)
	v_mfma_f32_32x32x16_bf16 v[32:47], v[66:69], v[82:85], v[32:47]
	ds_read_b64_tr_b16 v[82:83], v205 offset:0x400
	ds_read_b64_tr_b16 v[84:85], v205 offset:0xc00
	v_mfma_f32_32x32x16_bf16 v[32:47], v[70:73], v[86:89], v[32:47]
	ds_read_b64_tr_b16 v[86:87], v205 offset:0x1400
	ds_read_b64_tr_b16 v[88:89], v205 offset:0x1c00
	v_mfma_f32_32x32x16_bf16 v[32:47], v[74:77], v[90:93], v[32:47]
	ds_read_b64_tr_b16 v[90:91], v205 offset:0x2400
	ds_read_b64_tr_b16 v[92:93], v205 offset:0x2c00
	v_mfma_f32_32x32x16_bf16 v[32:47], v[78:81], v[94:97], v[32:47]
	ds_read_b64_tr_b16 v[94:95], v205 offset:0x3400
	ds_read_b64_tr_b16 v[96:97], v205 offset:0x3c00
	s_waitcnt lgkmcnt(0)
	v_mfma_f32_32x32x16_bf16 v[16:31], v[66:69], v[82:85], v[16:31]
	ds_read_b64_tr_b16 v[82:83], v205 offset:0x600
	ds_read_b64_tr_b16 v[84:85], v205 offset:0xe00
	v_mfma_f32_32x32x16_bf16 v[16:31], v[70:73], v[86:89], v[16:31]
	ds_read_b64_tr_b16 v[86:87], v205 offset:0x1600
	ds_read_b64_tr_b16 v[88:89], v205 offset:0x1e00
	v_mfma_f32_32x32x16_bf16 v[16:31], v[74:77], v[90:93], v[16:31]
	ds_read_b64_tr_b16 v[90:91], v205 offset:0x2600
	ds_read_b64_tr_b16 v[92:93], v205 offset:0x2e00
	v_mfma_f32_32x32x16_bf16 v[16:31], v[78:81], v[94:97], v[16:31]
	ds_read_b64_tr_b16 v[94:95], v205 offset:0x3600
	ds_read_b64_tr_b16 v[96:97], v205 offset:0x3e00
	s_waitcnt lgkmcnt(0)
	v_mfma_f32_32x32x16_bf16 v[0:15], v[66:69], v[82:85], v[0:15]
	v_mfma_f32_32x32x16_bf16 v[0:15], v[70:73], v[86:89], v[0:15]
	v_mfma_f32_32x32x16_bf16 v[0:15], v[74:77], v[90:93], v[0:15]
	v_mfma_f32_32x32x16_bf16 v[0:15], v[78:81], v[94:97], v[0:15]
	s_setprio 0
	v_and_b32_e32 v205, 0xfffeffff, v205
	v_and_b32_e32 v206, 0xfffeffff, v206
	v_and_b32_e32 v207, 0xfffeffff, v207
	v_and_b32_e32 v208, 0xfffeffff, v208
	v_and_b32_e32 v209, 0xfffeffff, v209
	v_and_b32_e32 v210, 0xfffeffff, v210
	v_and_b32_e32 v211, 0xfffeffff, v211
	v_and_b32_e32 v212, 0xfffeffff, v212
	v_and_b32_e32 v213, 0xfffeffff, v213
	v_cndmask_b32_e64 v66, 0, 1, s[0:1]
	v_cmp_ne_u32_e32 vcc, 0, v66
	s_cmp_lg_u64 vcc, 0
	s_cselect_b64 s[0:1], -1, 0
	v_cmp_eq_u32_e32 vcc, 0, v203
	s_and_b64 s[2:3], vcc, s[0:1]
	s_and_saveexec_b64 s[0:1], s[2:3]
	ds_write_b32 v153, v229 offset:51200
	s_or_b64 exec, exec, s[0:1]
	s_waitcnt vmcnt(0) lgkmcnt(0)
	s_barrier
	ds_read_b32 v66, v153 offset:51200
	s_mov_b32 s9, s49
	s_waitcnt lgkmcnt(0)
	s_barrier
	v_cmp_eq_u32_e32 vcc, 0, v66
	s_cbranch_vccnz .LBB0_824
	v_mbcnt_lo_u32_b32 v0, -1, 0
	v_mbcnt_hi_u32_b32 v0, -1, v0
	v_mov_b64_e32 v[14:15], s[94:95]
	v_add_u32_e32 v35, s33, v0
	v_mov_b32_e32 v33, v153
	v_ashrrev_i32_e32 v0, 1, v35
	v_and_b32_e32 v34, 31, v35
	v_and_b32_e32 v0, 0xffffffe0, v0
	v_ashrrev_i32_e32 v1, 31, v0
	v_or_b32_e32 v152, s8, v34
	v_ashrrev_i32_e32 v148, 3, v35
	v_lshlrev_b32_e32 v16, 3, v35
	v_lshl_add_u64 v[12:13], v[152:153], 0, v[0:1]
	v_and_b32_e32 v0, 56, v16
	v_ashrrev_i32_e32 v149, 31, v148
	v_lshlrev_b32_e32 v32, 1, v0
	v_lshl_add_u64 v[0:1], v[148:149], 0, s[10:11]
	v_ashrrev_i32_e32 v150, 4, v35
	v_mad_u64_u32 v[2:3], s[0:1], v0, s60, v[14:15]
	v_mad_i32_i24 v3, v1, s60, v3
	v_ashrrev_i32_e32 v151, 31, v150
	v_lshl_add_u64 v[0:1], v[2:3], 0, v[32:33]
	v_lshl_add_u64 v[2:3], v[150:151], 0, s[10:11]
	v_mov_b64_e32 v[4:5], s[70:71]
	v_mad_u64_u32 v[4:5], s[0:1], v2, s60, v[4:5]
	v_and_b32_e32 v6, 0x78, v16
	v_mad_i32_i24 v5, v3, s60, v5
	s_mov_b32 s91, s49
	v_lshl_add_u64 v[2:3], v[4:5], 0, s[90:91]
	v_lshlrev_b32_e32 v152, 1, v6
	v_lshl_add_u64 v[8:9], v[2:3], 0, v[152:153]
	global_load_dwordx4 v[0:3], v[0:1], off offset:3072
	s_nop 0
	global_load_dwordx4 v[4:7], v[8:9], off
	v_add_co_u32_e32 v8, vcc, s58, v8
	v_mad_u64_u32 v[14:15], s[0:1], v12, s60, v[14:15]
	s_nop 0
	v_addc_co_u32_e32 v9, vcc, 0, v9, vcc
	global_load_dwordx4 v[8:11], v[8:9], off
	v_lshrrev_b32_e32 v17, 1, v35
	v_mad_i32_i24 v15, v13, s60, v15
	v_and_b32_e32 v146, 16, v17
	v_mov_b32_e32 v147, v153
	v_lshl_add_u64 v[12:13], v[14:15], 0, v[146:147]
	global_load_dwordx4 v[116:119], v[12:13], off offset:2048
	global_load_dwordx4 v[120:123], v[12:13], off offset:2080
	global_load_dwordx4 v[124:127], v[12:13], off offset:2112
	global_load_dwordx4 v[112:115], v[12:13], off offset:2144
	v_and_b32_e32 v19, 0xfffff0, v150
	v_lshlrev_b32_e32 v20, 1, v150
	v_lshrrev_b32_e32 v21, 1, v150
	v_and_b32_e32 v23, 3, v150
	v_add_u32_e32 v24, 32, v150
	v_and_b32_e32 v14, 0x70, v35
	v_lshlrev_b32_e32 v18, 7, v148
	v_bfe_u32 v22, v16, 5, 2
	v_and_b32_e32 v33, 0x70, v16
	v_and_or_b32 v16, v20, 8, v19
	v_and_or_b32 v19, v21, 4, v23
	v_and_b32_e32 v20, 0xfffff0, v24
	v_lshlrev_b32_e32 v21, 1, v24
	v_lshl_add_u32 v40, v34, 7, 0
	v_bitop3_b32 v17, v17, v33, 16 bitop3:0x6c
	v_bitop3_b32 v14, v32, v18, v14 bitop3:0xde
	v_lshrrev_b32_e32 v16, 1, v16
	v_lshlrev_b32_e32 v18, 6, v19
	v_and_or_b32 v19, v21, 8, v20
	v_add_u32_e32 v171, v40, v17
	v_or_b32_e32 v16, v16, v22
	v_lshrrev_b32_e32 v17, 1, v19
	v_lshlrev_b32_e32 v15, 4, v35
	v_add_u32_e32 v172, 0, v14
	v_lshlrev_b32_e32 v14, 9, v16
	v_or_b32_e32 v16, v17, v22
	v_and_b32_e32 v15, 48, v15
	v_lshlrev_b32_e32 v12, 9, v16
	v_or3_b32 v14, v14, v18, v15
	v_or3_b32 v12, v12, v18, v15
	v_add_u32_e32 v173, 0, v14
	v_add_u32_e32 v174, 0, v12
	v_bitop3_b32 v20, v146, v33, 32 bitop3:0x36
	v_add_u32_e32 v175, v40, v20
	v_bitop3_b32 v41, v146, v33, 64 bitop3:0x36
	v_add_u32_e32 v176, v40, v41
	v_bitop3_b32 v33, v146, v33, s88 bitop3:0x36
	v_add_u32_e32 v177, v40, v33
	s_waitcnt vmcnt(6)
	ds_write_b128 v172, v[0:3] offset:32768
	s_waitcnt vmcnt(5)
	ds_write_b128 v173, v[4:7]
	s_waitcnt vmcnt(4)
	ds_write_b128 v174, v[8:11]
	s_waitcnt lgkmcnt(0)
	s_barrier
	ds_read_b128 v[0:3], v171 offset:32768
	ds_read_b128 v[16:19], v171 offset:36864
	ds_read_b128 v[36:39], v175 offset:32768
	s_waitcnt vmcnt(3) lgkmcnt(2)
	v_mfma_f32_32x32x16_bf16 v[0:15], v[0:3], v[116:119], 0
	s_waitcnt vmcnt(2) lgkmcnt(0)
	v_mfma_f32_32x32x16_bf16 v[0:15], v[36:39], v[120:123], v[0:15]
	ds_read_b128 v[36:39], v175 offset:36864
	v_mfma_f32_32x32x16_bf16 v[16:31], v[16:19], v[116:119], 0
	s_waitcnt lgkmcnt(0)
	v_mfma_f32_32x32x16_bf16 v[16:31], v[36:39], v[120:123], v[16:31]
	ds_read_b128 v[36:39], v176 offset:32768
	s_waitcnt vmcnt(1) lgkmcnt(0)
	v_mfma_f32_32x32x16_bf16 v[0:15], v[36:39], v[124:127], v[0:15]
	ds_read_b128 v[36:39], v176 offset:36864
	s_waitcnt lgkmcnt(0)
	v_mfma_f32_32x32x16_bf16 v[16:31], v[36:39], v[124:127], v[16:31]
	ds_read_b128 v[36:39], v177 offset:32768
	s_waitcnt vmcnt(0) lgkmcnt(0)
	v_mfma_f32_32x32x16_bf16 v[0:15], v[36:39], v[112:115], v[0:15]
	ds_read_b128 v[36:39], v177 offset:36864
	s_waitcnt lgkmcnt(0)
	v_mfma_f32_32x32x16_bf16 v[16:31], v[36:39], v[112:115], v[16:31]
	s_nop 8
	v_max_f32_e32 v33, v1, v1
	v_max_f32_e32 v36, v0, v0
	v_max_f32_e32 v33, v36, v33
	v_max3_f32 v33, v33, v2, v3
	v_max3_f32 v33, v33, v4, v5
	v_max3_f32 v33, v33, v6, v7
	v_max3_f32 v33, v33, v8, v9
	v_max3_f32 v33, v33, v10, v11
	v_max3_f32 v33, v33, v12, v13
	v_max3_f32 v33, v33, v14, v15
	v_max3_f32 v33, v33, v16, v17
	v_max3_f32 v33, v33, v18, v19
	v_max3_f32 v33, v33, v20, v21
	v_max3_f32 v33, v33, v22, v23
	v_max3_f32 v33, v33, v24, v25
	v_max3_f32 v33, v33, v26, v27
	v_max3_f32 v33, v33, v28, v29
	v_max3_f32 v33, v33, v30, v31
	v_mov_b32_e32 v36, v33
	s_nop 1
	v_permlane32_swap_b32_e32 v33, v36
	v_max_f32_e32 v36, v36, v36
	v_max_f32_e32 v33, v33, v33
	v_max_f32_e32 v33, v33, v36
	v_add_f32_e32 v36, 0x7149f2ca, v33
	v_cmp_ge_f32_e32 vcc, s66, v36
	s_cmp_eq_u64 vcc, exec
	s_cbranch_scc0 .LBB0_865
	v_mov_b32_e32 v144, 0xf149f2ca
	v_mov_b32_e32 v178, 1.0
